# prep phase state-copy units: all 12/13 row loads issued up front with counted waits (was load, vmcnt(0) incl. previous store, convert, store per piece), on top of v74
# speedup vs baseline: 1.0042x; 1.0042x over previous
.LBB0_1945:
	v_lshl_add_u64 v[6:7], s[8:9], 0, v[2:3]
	v_lshl_add_u64 v[8:9], s[10:11], 0, v[4:5]
	s_mov_b64 s[8:9], 0x1000
	v_lshl_add_u64 v[166:167], v[6:7], 0, s[8:9]
	v_lshl_add_u64 v[168:169], v[8:9], 0, s[8:9]
	v_lshl_add_u64 v[170:171], v[168:169], 0, s[8:9]
	v_lshl_add_u64 v[172:173], v[170:171], 0, s[8:9]
	global_load_dwordx2 v[140:141], v[6:7], off
	global_load_dwordx2 v[142:143], v[6:7], off offset:512
	global_load_dwordx2 v[144:145], v[6:7], off offset:1024
	global_load_dwordx2 v[146:147], v[6:7], off offset:1536
	global_load_dwordx2 v[148:149], v[6:7], off offset:2048
	global_load_dwordx2 v[150:151], v[6:7], off offset:2560
	global_load_dwordx2 v[152:153], v[6:7], off offset:3072
	global_load_dwordx2 v[154:155], v[6:7], off offset:3584
	global_load_dwordx2 v[156:157], v[166:167], off
	global_load_dwordx2 v[158:159], v[166:167], off offset:512
	global_load_dwordx2 v[160:161], v[166:167], off offset:1024
	global_load_dwordx2 v[162:163], v[166:167], off offset:1536
	s_cmpk_lt_u32 s12, 0x340
	s_cbranch_scc1 .Lpc_12
	global_load_dwordx2 v[164:165], v[166:167], off offset:2048
.Lpc_12:
	s_waitcnt vmcnt(11)
	v_lshlrev_b32_e32 v10, 16, v140
	v_and_b32_e32 v11, 0xffff0000, v140
	v_lshlrev_b32_e32 v12, 16, v141
	v_and_b32_e32 v13, 0xffff0000, v141
	global_store_dwordx4 v[8:9], v[10:13], off
	s_waitcnt vmcnt(11)
	v_lshlrev_b32_e32 v174, 16, v142
	v_and_b32_e32 v175, 0xffff0000, v142
	v_lshlrev_b32_e32 v176, 16, v143
	v_and_b32_e32 v177, 0xffff0000, v143
	global_store_dwordx4 v[8:9], v[174:177], off offset:1024
	s_waitcnt vmcnt(11)
	v_lshlrev_b32_e32 v10, 16, v144
	v_and_b32_e32 v11, 0xffff0000, v144
	v_lshlrev_b32_e32 v12, 16, v145
	v_and_b32_e32 v13, 0xffff0000, v145
	global_store_dwordx4 v[8:9], v[10:13], off offset:2048
	s_waitcnt vmcnt(11)
	v_lshlrev_b32_e32 v174, 16, v146
	v_and_b32_e32 v175, 0xffff0000, v146
	v_lshlrev_b32_e32 v176, 16, v147
	v_and_b32_e32 v177, 0xffff0000, v147
	global_store_dwordx4 v[8:9], v[174:177], off offset:3072
	s_waitcnt vmcnt(11)
	v_lshlrev_b32_e32 v10, 16, v148
	v_and_b32_e32 v11, 0xffff0000, v148
	v_lshlrev_b32_e32 v12, 16, v149
	v_and_b32_e32 v13, 0xffff0000, v149
	global_store_dwordx4 v[168:169], v[10:13], off
	s_waitcnt vmcnt(11)
	v_lshlrev_b32_e32 v174, 16, v150
	v_and_b32_e32 v175, 0xffff0000, v150
	v_lshlrev_b32_e32 v176, 16, v151
	v_and_b32_e32 v177, 0xffff0000, v151
	global_store_dwordx4 v[168:169], v[174:177], off offset:1024
	s_waitcnt vmcnt(11)
	v_lshlrev_b32_e32 v10, 16, v152
	v_and_b32_e32 v11, 0xffff0000, v152
	v_lshlrev_b32_e32 v12, 16, v153
	v_and_b32_e32 v13, 0xffff0000, v153
	global_store_dwordx4 v[168:169], v[10:13], off offset:2048
	s_waitcnt vmcnt(11)
	v_lshlrev_b32_e32 v174, 16, v154
	v_and_b32_e32 v175, 0xffff0000, v154
	v_lshlrev_b32_e32 v176, 16, v155
	v_and_b32_e32 v177, 0xffff0000, v155
	global_store_dwordx4 v[168:169], v[174:177], off offset:3072
	s_waitcnt vmcnt(11)
	v_lshlrev_b32_e32 v10, 16, v156
	v_and_b32_e32 v11, 0xffff0000, v156
	v_lshlrev_b32_e32 v12, 16, v157
	v_and_b32_e32 v13, 0xffff0000, v157
	global_store_dwordx4 v[170:171], v[10:13], off
	s_waitcnt vmcnt(11)
	v_lshlrev_b32_e32 v174, 16, v158
	v_and_b32_e32 v175, 0xffff0000, v158
	v_lshlrev_b32_e32 v176, 16, v159
	v_and_b32_e32 v177, 0xffff0000, v159
	global_store_dwordx4 v[170:171], v[174:177], off offset:1024
	s_waitcnt vmcnt(11)
	v_lshlrev_b32_e32 v10, 16, v160
	v_and_b32_e32 v11, 0xffff0000, v160
	v_lshlrev_b32_e32 v12, 16, v161
	v_and_b32_e32 v13, 0xffff0000, v161
	global_store_dwordx4 v[170:171], v[10:13], off offset:2048
	s_waitcnt vmcnt(11)
	v_lshlrev_b32_e32 v174, 16, v162
	v_and_b32_e32 v175, 0xffff0000, v162
	v_lshlrev_b32_e32 v176, 16, v163
	v_and_b32_e32 v177, 0xffff0000, v163
	global_store_dwordx4 v[170:171], v[174:177], off offset:3072
	s_cmpk_lt_u32 s12, 0x340
	s_cbranch_scc1 .Lpc_done
	s_waitcnt vmcnt(12)
	v_lshlrev_b32_e32 v10, 16, v164
	v_and_b32_e32 v11, 0xffff0000, v164
	v_lshlrev_b32_e32 v12, 16, v165
	v_and_b32_e32 v13, 0xffff0000, v165
	global_store_dwordx4 v[172:173], v[10:13], off
.Lpc_done:
	s_mov_b64 s[8:9], 0
	s_mov_b64 s[10:11], 0x400
	s_or_b64 exec, exec, s[8:9]
	s_add_i32 s14, s14, s50
	s_cmpk_gt_i32 s14, 0x20f
	s_cbranch_scc0 .LBB0_1933
